# attention epilogue: 16 gate/gain loads hoisted above X exchange, single wait
# speedup vs baseline: 1.0125x; 1.0125x over previous
; #define GAS __attribute__((address_space(1)))
; __device__ __forceinline__ void mix_attn(const bf16* h, const bf16* VT, const float* dl, int layer, const float* ng, bf16* ycat, char* lds, int wg, int G) {
;     ...
;             if (st == 0) {
;                 float ss = 0.f;
; #pragma unroll
;                 for (int blk = 0; blk < 8; ++blk)
; #pragma unroll
;                     for (int r = 0; r < 4; ++r) { const float o = oacc[blk][r] * inv - X[(rs * 32 + blk * 4 + r) * 64 + lane]; oacc[blk][r] = o; ss += o * o; }
;                 ss += __shfl_xor(ss, 16); ss += __shfl_xor(ss, 32);
;                 const float rsc = rsqrtf(ss * (1.f / 128.f) + RMS_EPS) * (1.f - lam_init);
;                 const size_t m = mrow0 + q0 + 16 * rs + li;
;                 const GAS bf16* gp = (const GAS bf16*)h + m * NH + C_GC + hh * 128 + 4 * g; GAS bf16* yp = (GAS bf16*)ycat + m * DM + Y_C + hh * 128 + 4 * g; const GAS float* ngp = (const GAS float*)ng + hh * 128 + 4 * g;
; #pragma unroll
;                 for (int blk = 0; blk < 8; ++blk) { const v2u gt = *(const GAS v2u*)(gp + 16 * blk); const pg8::f32x4 nv = *(const GAS pg8::f32x4*)(ngp + 16 * blk);
.LBB0_594:
	s_andn2_b64 vcc, exec, s[76:77]
	s_waitcnt lgkmcnt(0)
	s_barrier
	s_cbranch_vccnz .LBB0_556
	s_add_i32 s1, s25, s1
	v_lshl_add_u32 v48, v147, 2, s1
	s_mov_b32 s1, s29
	v_mov_b32_e32 v167, v169
	v_lshl_add_u64 v[106:107], v[198:199], 0, s[0:1]
	v_lshl_add_u64 v[106:107], v[106:107], 0, v[166:167]
	v_add_co_u32_e32 v106, vcc, 0x3400, v106
	s_nop 1
	v_addc_co_u32_e32 v107, vcc, 0, v107, vcc
	global_load_dwordx4 v[50:53], v[180:181], off
	global_load_dwordx4 v[54:57], v[180:181], off offset:64
	global_load_dwordx4 v[58:61], v[180:181], off offset:128
	global_load_dwordx4 v[62:65], v[180:181], off offset:192
	global_load_dwordx4 v[66:69], v[180:181], off offset:256
	global_load_dwordx4 v[70:73], v[180:181], off offset:320
	global_load_dwordx4 v[74:77], v[180:181], off offset:384
	global_load_dwordx4 v[78:81], v[180:181], off offset:448
	global_load_dwordx2 v[82:83], v[106:107], off
	global_load_dwordx2 v[84:85], v[106:107], off offset:32
	global_load_dwordx2 v[86:87], v[106:107], off offset:64
	global_load_dwordx2 v[96:97], v[106:107], off offset:96
	global_load_dwordx2 v[98:99], v[106:107], off offset:128
	global_load_dwordx2 v[100:101], v[106:107], off offset:160
	global_load_dwordx2 v[102:103], v[106:107], off offset:192
	global_load_dwordx2 v[104:105], v[106:107], off offset:224
	ds_read2st64_b32 v[20:21], v48 offset1:1
	ds_read2st64_b32 v[22:23], v48 offset0:2 offset1:3
	ds_read2st64_b32 v[24:25], v48 offset0:4 offset1:5
	ds_read2st64_b32 v[28:29], v48 offset0:6 offset1:7
	ds_read2st64_b32 v[30:31], v48 offset0:10 offset1:11
	s_waitcnt lgkmcnt(4)
	v_fma_f32 v19, v45, v16, -v21
	s_waitcnt lgkmcnt(3)
	v_fma_f32 v21, v47, v16, -v23
	s_waitcnt lgkmcnt(2)
	v_fma_f32 v23, v41, v16, -v25
	s_waitcnt lgkmcnt(1)
	v_fma_f32 v27, v42, v16, -v28
	v_fma_f32 v25, v43, v16, -v29
	ds_read2st64_b32 v[28:29], v48 offset0:8 offset1:9
	v_fma_f32 v24, v40, v16, -v24
	v_fma_f32 v20, v44, v16, -v20
	v_mul_f32_e32 v44, v19, v19
	v_fmac_f32_e32 v44, v20, v20
	s_waitcnt lgkmcnt(0)
	v_fma_f32 v28, v36, v16, -v28
	v_fma_f32 v26, v37, v16, -v29
	v_fma_f32 v37, v38, v16, -v30
	v_fma_f32 v36, v39, v16, -v31
	ds_read2st64_b32 v[30:31], v48 offset0:12 offset1:13
	v_fma_f32 v22, v46, v16, -v22
	v_fmac_f32_e32 v44, v22, v22
	v_fmac_f32_e32 v44, v21, v21
	v_fmac_f32_e32 v44, v24, v24
	s_waitcnt lgkmcnt(0)
	v_fma_f32 v40, v32, v16, -v30
	v_fma_f32 v39, v33, v16, -v31
	ds_read2st64_b32 v[30:31], v48 offset0:14 offset1:15
	v_fmac_f32_e32 v44, v23, v23
	v_fmac_f32_e32 v44, v27, v27
	v_fmac_f32_e32 v44, v25, v25
	v_fmac_f32_e32 v44, v28, v28
	s_waitcnt lgkmcnt(0)
	v_fma_f32 v42, v34, v16, -v30
	v_fma_f32 v41, v35, v16, -v31
	ds_read2st64_b32 v[30:31], v48 offset0:16 offset1:17
	v_fmac_f32_e32 v44, v26, v26
	v_fmac_f32_e32 v44, v37, v37
	v_fmac_f32_e32 v44, v36, v36
	v_fmac_f32_e32 v44, v40, v40
	s_waitcnt lgkmcnt(0)
	v_fma_f32 v38, v12, v16, -v30
	v_fma_f32 v35, v13, v16, -v31
	ds_read2st64_b32 v[12:13], v48 offset0:18 offset1:19
	v_fmac_f32_e32 v44, v39, v39
	v_fmac_f32_e32 v44, v42, v42
	v_fmac_f32_e32 v44, v41, v41
	v_fmac_f32_e32 v44, v38, v38
	s_waitcnt lgkmcnt(0)
	v_fma_f32 v34, v14, v16, -v12
	v_fma_f32 v33, v15, v16, -v13
	ds_read2st64_b32 v[12:13], v48 offset0:20 offset1:21
	v_fmac_f32_e32 v44, v35, v35
	v_fmac_f32_e32 v44, v34, v34
	v_fmac_f32_e32 v44, v33, v33
	s_mov_b32 s1, s29
	s_waitcnt lgkmcnt(0)
	v_fma_f32 v32, v8, v16, -v12
	v_fma_f32 v31, v9, v16, -v13
	ds_read2st64_b32 v[8:9], v48 offset0:22 offset1:23
	v_fmac_f32_e32 v44, v32, v32
	v_fmac_f32_e32 v44, v31, v31
	v_mov_b32_e32 v167, v169
	s_waitcnt lgkmcnt(0)
	v_fma_f32 v30, v10, v16, -v8
	v_fma_f32 v29, v11, v16, -v9
	ds_read2st64_b32 v[8:9], v48 offset0:24 offset1:25
	v_fmac_f32_e32 v44, v30, v30
	v_fmac_f32_e32 v44, v29, v29
	s_waitcnt lgkmcnt(0)
	v_pk_fma_f32 v[14:15], v[4:5], v[16:17], v[8:9] op_sel_hi:[1,0,1] neg_lo:[0,0,1] neg_hi:[0,0,1]
	s_nop 0
	v_pk_mul_f32 v[4:5], v[14:15], v[14:15]
	s_nop 0
	v_add_f32_e32 v4, v44, v4
	v_add_f32_e32 v8, v4, v5
	ds_read2st64_b32 v[4:5], v48 offset0:26 offset1:27
	s_waitcnt lgkmcnt(0)
	v_pk_fma_f32 v[12:13], v[6:7], v[16:17], v[4:5] op_sel_hi:[1,0,1] neg_lo:[0,0,1] neg_hi:[0,0,1]
	s_nop 0
	v_pk_mul_f32 v[4:5], v[12:13], v[12:13]
	s_nop 0
	v_add_f32_e32 v4, v8, v4
	v_add_f32_e32 v8, v4, v5
	ds_read2st64_b32 v[4:5], v48 offset0:28 offset1:29
	s_waitcnt lgkmcnt(0)
	v_pk_fma_f32 v[6:7], v[0:1], v[16:17], v[4:5] op_sel_hi:[1,0,1] neg_lo:[0,0,1] neg_hi:[0,0,1]
	s_nop 0
	v_pk_mul_f32 v[0:1], v[6:7], v[6:7]
	s_nop 0
	v_add_f32_e32 v0, v8, v0
	v_add_f32_e32 v8, v0, v1
	ds_read2st64_b32 v[0:1], v48 offset0:30 offset1:31
	s_waitcnt lgkmcnt(0)
	v_pk_fma_f32 v[4:5], v[2:3], v[16:17], v[0:1] op_sel_hi:[1,0,1] neg_lo:[0,0,1] neg_hi:[0,0,1]
	s_nop 0
	v_pk_mul_f32 v[0:1], v[4:5], v[4:5]
	v_lshlrev_b64 v[2:3], 12, v[196:197]
	v_add_f32_e32 v0, v8, v0
	v_add_f32_e32 v0, v0, v1
	ds_bpermute_b32 v1, v17, v0
	v_lshl_add_u64 v[8:9], v[194:195], 0, v[2:3]
	s_waitcnt lgkmcnt(0)
	v_add_f32_e32 v0, v0, v1
	ds_bpermute_b32 v1, v18, v0
	s_waitcnt lgkmcnt(0)
; #define GAS __attribute__((address_space(1)))
; __device__ __forceinline__ unsigned pk2(float lo, float hi) { unsigned r; asm("v_cvt_pk_bf16_f32 %0, %1, %2" : "=v"(r) : "v"(lo), "v"(hi)); return r; }
; __device__ __forceinline__ void mix_attn(const bf16* h, const bf16* VT, const float* dl, int layer, const float* ng, bf16* ycat, char* lds, int wg, int G) {
;     ...
;                 ss += __shfl_xor(ss, 16); ss += __shfl_xor(ss, 32);
;                 const float rsc = rsqrtf(ss * (1.f / 128.f) + RMS_EPS) * (1.f - lam_init);
;                 const size_t m = mrow0 + q0 + 16 * rs + li;
;                 const GAS bf16* gp = (const GAS bf16*)h + m * NH + C_GC + hh * 128 + 4 * g; GAS bf16* yp = (GAS bf16*)ycat + m * DM + Y_C + hh * 128 + 4 * g; const GAS float* ngp = (const GAS float*)ng + hh * 128 + 4 * g;
; #pragma unroll
;                 for (int blk = 0; blk < 8; ++blk) { const v2u gt = *(const GAS v2u*)(gp + 16 * blk); const pg8::f32x4 nv = *(const GAS pg8::f32x4*)(ngp + 16 * blk);
;                     v2u w; w.x = pk2(oacc[blk][0] * rsc * nv[0] * __uint_as_float(gt.x << 16), oacc[blk][1] * rsc * nv[1] * __uint_as_float(gt.x & 0xffff0000u));
;                     w.y = pk2(oacc[blk][2] * rsc * nv[2] * __uint_as_float(gt.y << 16), oacc[blk][3] * rsc * nv[3] * __uint_as_float(gt.y & 0xffff0000u));
;                     *(GAS v2u*)(yp + 16 * blk) = w; }
	v_add_f32_e32 v0, v0, v1
	v_fmamk_f32 v0, v0, 0x3c000000, v215
	v_cmp_gt_f32_e32 vcc, s93, v0
	v_mul_f32_e32 v1, 0x4b800000, v0
	s_nop 0
	v_cndmask_b32_e32 v0, v0, v1, vcc
	v_rsq_f32_e32 v0, v0
	s_nop 0
	v_mul_f32_e32 v1, 0x45800000, v0
	v_cndmask_b32_e32 v0, v0, v1, vcc
	v_mul_f32_e32 v18, v226, v0
	s_waitcnt vmcnt(0)
	v_mul_f32_e32 v0, v20, v18
	v_mul_f32_e32 v1, v19, v18
	v_mul_f32_e32 v2, v22, v18
	v_mul_f32_e32 v3, v21, v18
	v_mul_f32_e32 v0, v0, v50
	v_mul_f32_e32 v1, v1, v51
	v_mul_f32_e32 v2, v2, v52
	v_mul_f32_e32 v3, v3, v53
	v_lshlrev_b32_e32 v16, 16, v82
	v_and_b32_e32 v17, 0xffff0000, v82
	v_mul_f32_e32 v0, v0, v16
	v_mul_f32_e32 v1, v1, v17
	v_lshlrev_b32_e32 v16, 16, v83
	v_and_b32_e32 v17, 0xffff0000, v83
	v_mul_f32_e32 v2, v2, v16
	v_mul_f32_e32 v3, v3, v17
	v_cvt_pk_bf16_f32 v0, v0, v1
	v_cvt_pk_bf16_f32 v1, v2, v3
	global_store_dwordx2 v[8:9], v[0:1], off offset:2048
	v_mul_f32_e32 v0, v24, v18
	v_mul_f32_e32 v1, v23, v18
	v_mul_f32_e32 v2, v27, v18
	v_mul_f32_e32 v3, v25, v18
	v_mul_f32_e32 v0, v0, v54
	v_mul_f32_e32 v1, v1, v55
	v_mul_f32_e32 v2, v2, v56
	v_mul_f32_e32 v3, v3, v57
	v_lshlrev_b32_e32 v16, 16, v84
	v_and_b32_e32 v17, 0xffff0000, v84
	v_mul_f32_e32 v0, v0, v16
	v_mul_f32_e32 v1, v1, v17
	v_lshlrev_b32_e32 v16, 16, v85
	v_and_b32_e32 v17, 0xffff0000, v85
	v_mul_f32_e32 v2, v2, v16
	v_mul_f32_e32 v3, v3, v17
	v_cvt_pk_bf16_f32 v0, v0, v1
	v_cvt_pk_bf16_f32 v1, v2, v3
	global_store_dwordx2 v[8:9], v[0:1], off offset:2080
	v_mul_f32_e32 v0, v28, v18
	v_mul_f32_e32 v1, v26, v18
	v_mul_f32_e32 v2, v37, v18
	v_mul_f32_e32 v3, v36, v18
	v_mul_f32_e32 v0, v0, v58
	v_mul_f32_e32 v1, v1, v59
	v_mul_f32_e32 v2, v2, v60
	v_mul_f32_e32 v3, v3, v61
	v_lshlrev_b32_e32 v16, 16, v86
	v_and_b32_e32 v17, 0xffff0000, v86
	v_mul_f32_e32 v0, v0, v16
	v_mul_f32_e32 v1, v1, v17
	v_lshlrev_b32_e32 v16, 16, v87
	v_and_b32_e32 v17, 0xffff0000, v87
	v_mul_f32_e32 v2, v2, v16
	v_mul_f32_e32 v3, v3, v17
	v_cvt_pk_bf16_f32 v0, v0, v1
	v_cvt_pk_bf16_f32 v1, v2, v3
	global_store_dwordx2 v[8:9], v[0:1], off offset:2112
	v_mul_f32_e32 v0, v40, v18
	v_mul_f32_e32 v1, v39, v18
	v_mul_f32_e32 v2, v42, v18
	v_mul_f32_e32 v3, v41, v18
	v_mul_f32_e32 v0, v0, v62
	v_mul_f32_e32 v1, v1, v63
	v_mul_f32_e32 v2, v2, v64
	v_mul_f32_e32 v3, v3, v65
	v_lshlrev_b32_e32 v16, 16, v96
	v_and_b32_e32 v17, 0xffff0000, v96
	v_mul_f32_e32 v0, v0, v16
	v_mul_f32_e32 v1, v1, v17
	v_lshlrev_b32_e32 v16, 16, v97
	v_and_b32_e32 v17, 0xffff0000, v97
	v_mul_f32_e32 v2, v2, v16
	v_mul_f32_e32 v3, v3, v17
	v_cvt_pk_bf16_f32 v0, v0, v1
	v_cvt_pk_bf16_f32 v1, v2, v3
	global_store_dwordx2 v[8:9], v[0:1], off offset:2144
	v_mul_f32_e32 v0, v38, v18
	v_mul_f32_e32 v1, v35, v18
	v_mul_f32_e32 v2, v34, v18
	v_mul_f32_e32 v3, v33, v18
	v_mul_f32_e32 v0, v0, v66
	v_mul_f32_e32 v1, v1, v67
	v_mul_f32_e32 v2, v2, v68
	v_mul_f32_e32 v3, v3, v69
	v_lshlrev_b32_e32 v16, 16, v98
	v_and_b32_e32 v17, 0xffff0000, v98
	v_mul_f32_e32 v0, v0, v16
	v_mul_f32_e32 v1, v1, v17
	v_lshlrev_b32_e32 v16, 16, v99
	v_and_b32_e32 v17, 0xffff0000, v99
	v_mul_f32_e32 v2, v2, v16
	v_mul_f32_e32 v3, v3, v17
	v_cvt_pk_bf16_f32 v0, v0, v1
	v_cvt_pk_bf16_f32 v1, v2, v3
	global_store_dwordx2 v[8:9], v[0:1], off offset:2176
	v_mul_f32_e32 v0, v32, v18
	v_mul_f32_e32 v1, v31, v18
	v_mul_f32_e32 v2, v30, v18
	v_mul_f32_e32 v3, v29, v18
	v_mul_f32_e32 v0, v0, v70
	v_mul_f32_e32 v1, v1, v71
	v_mul_f32_e32 v2, v2, v72
	v_mul_f32_e32 v3, v3, v73
	v_lshlrev_b32_e32 v16, 16, v100
	v_and_b32_e32 v17, 0xffff0000, v100
	v_mul_f32_e32 v0, v0, v16
	v_mul_f32_e32 v1, v1, v17
	v_lshlrev_b32_e32 v16, 16, v101
	v_and_b32_e32 v17, 0xffff0000, v101
	v_mul_f32_e32 v2, v2, v16
	v_mul_f32_e32 v3, v3, v17
	v_cvt_pk_bf16_f32 v0, v0, v1
	v_cvt_pk_bf16_f32 v1, v2, v3
	global_store_dwordx2 v[8:9], v[0:1], off offset:2208
	v_mul_f32_e32 v0, v14, v18
	v_mul_f32_e32 v1, v15, v18
	v_mul_f32_e32 v2, v12, v18
	v_mul_f32_e32 v3, v13, v18
	v_mul_f32_e32 v0, v0, v74
	v_mul_f32_e32 v1, v1, v75
	v_mul_f32_e32 v2, v2, v76
	v_mul_f32_e32 v3, v3, v77
	v_lshlrev_b32_e32 v16, 16, v102
	v_and_b32_e32 v17, 0xffff0000, v102
	v_mul_f32_e32 v0, v0, v16
	v_mul_f32_e32 v1, v1, v17
	v_lshlrev_b32_e32 v16, 16, v103
	v_and_b32_e32 v17, 0xffff0000, v103
	v_mul_f32_e32 v2, v2, v16
	v_mul_f32_e32 v3, v3, v17
	v_cvt_pk_bf16_f32 v0, v0, v1
	v_cvt_pk_bf16_f32 v1, v2, v3
	global_store_dwordx2 v[8:9], v[0:1], off offset:2240
	v_mul_f32_e32 v0, v6, v18
	v_mul_f32_e32 v1, v7, v18
	v_mul_f32_e32 v2, v4, v18
	v_mul_f32_e32 v3, v5, v18
	v_mul_f32_e32 v0, v0, v78
	v_mul_f32_e32 v1, v1, v79
	v_mul_f32_e32 v2, v2, v80
	v_mul_f32_e32 v3, v3, v81
	v_lshlrev_b32_e32 v16, 16, v104
	v_and_b32_e32 v17, 0xffff0000, v104
	v_mul_f32_e32 v0, v0, v16
	v_mul_f32_e32 v1, v1, v17
	v_lshlrev_b32_e32 v16, 16, v105
	v_and_b32_e32 v17, 0xffff0000, v105
	v_mul_f32_e32 v2, v2, v16
	v_mul_f32_e32 v3, v3, v17
	v_cvt_pk_bf16_f32 v0, v0, v1
	v_cvt_pk_bf16_f32 v1, v2, v3
	global_store_dwordx2 v[8:9], v[0:1], off offset:2272
	s_movk_i32 s0, 0x3000
	s_branch .LBB0_556
